# pool_item rewritten: all loads in flight, log-step window sums, 8-row half items
# speedup vs baseline: 1.1202x; 1.1202x over previous
; __device__ __forceinline__ unsigned pk_bf16(float lo, float hi) { unsigned r; asm volatile("v_cvt_pk_bf16_f32 %0, %1, %2" : "=v"(r) : "v"(lo), "v"(hi)); return r; }
; __device__ void pool_item(const Params& p, int l, int item, const int tid_in) {
;     ...
;     const int col = tid * 4, g = tid >> 7, w = 2 << g;
;     const float* u = (const float*)(pws(p) + OFF_U);
;     bf16_t* pooled = (bf16_t*)(pws(p) + OFF_POOLED);
;     f32x4 p_self = (f32x4){0.f, 0.f, 0.f, 0.f}, p_res = p_self, p_hist = p_self;
; #pragma unroll 1
;     for (int rr = 0; rr <= 16; ++rr) {
;         const int row = item * 16 + rr;
;         f32x4 self = (f32x4){0.f, 0.f, 0.f, 0.f}, sum = self, hcopy = self; float cnt = 1.f;
;         if (rr < 16) {
;             self = *(const f32x4*)(u + (size_t)row * D + col); sum = self;
;             if (row < MS) {
;                 const int b = row >> 3, t = row & 7;
;                 const float* hist = p.state_pool + ((size_t)l * 128 + b) * 15 * D + col;
;                 for (int i = 1; i < w; ++i) { const int tt = t - i;
;                     sum += tt >= 0 ? *(const f32x4*)(u + (size_t)(row - i) * D + col) : *(const f32x4*)(hist + (size_t)(15 + tt) * D); }
;                 cnt = (float)w;
;                 if (t < 7) hcopy = *(const f32x4*)(hist + (size_t)(8 + t) * D);
;             } else {
;                 const int pp = (row - MS) % LP;
;                 for (int i = 1; i < w; ++i) if (pp - i >= 0) sum += *(const f32x4*)(u + (size_t)(row - i) * D + col);
;                 cnt = (float)(w < pp + 1 ? w : pp + 1);
;             }
;         }
;         asm volatile("" ::: "memory");
;         if (rr > 0) {
;             const int prow = row - 1;
;             u32x2 o; o.x = pk_bf16(p_res[0], p_res[1]); o.y = pk_bf16(p_res[2], p_res[3]);
;             *(u32x2*)(pooled + (size_t)prow * D + col) = o;
;             if (prow < MS) {
;                 const int b = prow >> 3, t = prow & 7;
;                 float* np = pout(p) + O_PS + ((size_t)l * 128 + b) * 15 * D + col;
;                 *(f32x4*)(np + (size_t)(7 + t) * D) = p_self;
;                 if (t < 7) *(f32x4*)(np + (size_t)t * D) = p_hist;
.LBB0_452:
	s_cmpk_gt_i32 s38, 0x3ff
	s_cbranch_scc0 .LBB0_482
	s_cmpk_gt_u32 s38, 0x61f
	s_mov_b64 s[6:7], -1
	s_cbranch_scc0 .LBB0_484
	v_lshlrev_b32_e32 v2, 4, v244
	v_lshlrev_b32_e32 v3, 3, v244
	v_readfirstlane_b32 s0, v244
	v_readlane_b32 s10, v253, 39
	v_readlane_b32 s11, v253, 40
	s_lshr_b32 s19, s0, 7
	s_lshl_b32 s18, 2, s19
	s_mov_b32 s16, s36
.Lpool_half:
	s_cmpk_lt_u32 s16, 0x400
	s_cbranch_scc1 .Lpool_sample
	s_add_i32 s0, s16, 0xfffffc00
	s_mul_hi_u32 s15, s0, 0xfe03f81
	s_lshr_b32 s15, s15, 7
	s_mul_i32 s1, s15, 0x810
	s_sub_i32 s13, s0, s1
	s_add_i32 s0, s16, -15
	s_lshl_b32 s0, s0, 13
	s_add_u32 s6, s10, s0
	s_addc_u32 s7, s11, 0
	s_sub_i32 s12, 16, s18
	s_sub_i32 s0, 15, s13
	s_max_i32 s12, s12, s0
	s_cmp_lt_u32 s13, 16
	s_cbranch_scc0 .Lpool_loads
	v_mov_b32_e32 v8, 0
	v_mov_b32_e32 v9, 0
	v_mov_b32_e32 v10, 0
	v_mov_b32_e32 v11, 0
	v_mov_b32_e32 v12, 0
	v_mov_b32_e32 v13, 0
	v_mov_b32_e32 v14, 0
	v_mov_b32_e32 v15, 0
	v_mov_b32_e32 v16, 0
	v_mov_b32_e32 v17, 0
	v_mov_b32_e32 v18, 0
	v_mov_b32_e32 v19, 0
	v_mov_b32_e32 v20, 0
	v_mov_b32_e32 v21, 0
	v_mov_b32_e32 v22, 0
	v_mov_b32_e32 v23, 0
	v_mov_b32_e32 v24, 0
	v_mov_b32_e32 v25, 0
	v_mov_b32_e32 v26, 0
	v_mov_b32_e32 v27, 0
	v_mov_b32_e32 v28, 0
	v_mov_b32_e32 v29, 0
	v_mov_b32_e32 v30, 0
	v_mov_b32_e32 v31, 0
	v_mov_b32_e32 v32, 0
	v_mov_b32_e32 v33, 0
	v_mov_b32_e32 v34, 0
	v_mov_b32_e32 v35, 0
	v_mov_b32_e32 v36, 0
	v_mov_b32_e32 v37, 0
	v_mov_b32_e32 v38, 0
	v_mov_b32_e32 v39, 0
	v_mov_b32_e32 v40, 0
	v_mov_b32_e32 v41, 0
	v_mov_b32_e32 v42, 0
	v_mov_b32_e32 v43, 0
	v_mov_b32_e32 v44, 0
	v_mov_b32_e32 v45, 0
	v_mov_b32_e32 v46, 0
	v_mov_b32_e32 v47, 0
	v_mov_b32_e32 v48, 0
	v_mov_b32_e32 v49, 0
	v_mov_b32_e32 v50, 0
	v_mov_b32_e32 v51, 0
	v_mov_b32_e32 v52, 0
	v_mov_b32_e32 v53, 0
	v_mov_b32_e32 v54, 0
	v_mov_b32_e32 v55, 0
	v_mov_b32_e32 v56, 0
	v_mov_b32_e32 v57, 0
	v_mov_b32_e32 v58, 0
	v_mov_b32_e32 v59, 0
	v_mov_b32_e32 v60, 0
	v_mov_b32_e32 v61, 0
	v_mov_b32_e32 v62, 0
	v_mov_b32_e32 v63, 0
	v_mov_b32_e32 v64, 0
	v_mov_b32_e32 v65, 0
	v_mov_b32_e32 v66, 0
	v_mov_b32_e32 v67, 0
	s_branch .Lpool_loads
.Lpool_sample:
	s_lshr_b32 s15, s16, 3
	s_add_i32 s0, s22, s15
	s_mul_i32 s0, s0, 0x1e000
	s_add_u32 s6, s48, s0
	s_addc_u32 s7, s49, 0
	s_cmp_eq_u32 s18, 16
	s_cselect_b32 s12, 0, 8
	s_movk_i32 s13, 0x4000
.Lpool_loads:
	s_cmp_gt_i32 s12, 0
	s_cbranch_scc1 .Lpool_skipA
	s_mov_b64 s[8:9], s[6:7]
	global_load_dwordx4 v[8:11], v2, s[8:9]
	s_add_u32 s8, s8, 0x2000
	s_addc_u32 s9, s9, 0
	global_load_dwordx4 v[12:15], v2, s[8:9]
	s_add_u32 s8, s8, 0x2000
	s_addc_u32 s9, s9, 0
	global_load_dwordx4 v[16:19], v2, s[8:9]
	s_add_u32 s8, s8, 0x2000
	s_addc_u32 s9, s9, 0
	global_load_dwordx4 v[20:23], v2, s[8:9]
	s_add_u32 s8, s8, 0x2000
	s_addc_u32 s9, s9, 0
	global_load_dwordx4 v[24:27], v2, s[8:9]
	s_add_u32 s8, s8, 0x2000
	s_addc_u32 s9, s9, 0
	global_load_dwordx4 v[28:31], v2, s[8:9]
	s_add_u32 s8, s8, 0x2000
	s_addc_u32 s9, s9, 0
	global_load_dwordx4 v[32:35], v2, s[8:9]
.Lpool_skipA:
	s_cmp_gt_i32 s12, 7
	s_cbranch_scc1 .Lpool_skipB
	s_add_u32 s8, s6, 0xe000
	s_addc_u32 s9, s7, 0
	global_load_dwordx4 v[36:39], v2, s[8:9]
.Lpool_skipB:
	s_cmp_gt_i32 s12, 8
	s_cbranch_scc1 .Lpool_skipC
	s_add_u32 s8, s6, 0x10000
	s_addc_u32 s9, s7, 0
	global_load_dwordx4 v[40:43], v2, s[8:9]
	s_add_u32 s8, s8, 0x2000
	s_addc_u32 s9, s9, 0
	global_load_dwordx4 v[44:47], v2, s[8:9]
	s_add_u32 s8, s8, 0x2000
	s_addc_u32 s9, s9, 0
	global_load_dwordx4 v[48:51], v2, s[8:9]
	s_add_u32 s8, s8, 0x2000
	s_addc_u32 s9, s9, 0
	global_load_dwordx4 v[52:55], v2, s[8:9]
.Lpool_skipC:
	s_cmp_gt_i32 s12, 12
	s_cbranch_scc1 .Lpool_skipD
	s_add_u32 s8, s6, 0x18000
	s_addc_u32 s9, s7, 0
	global_load_dwordx4 v[56:59], v2, s[8:9]
	s_add_u32 s8, s8, 0x2000
	s_addc_u32 s9, s9, 0
	global_load_dwordx4 v[60:63], v2, s[8:9]
.Lpool_skipD:
	s_cmp_gt_i32 s12, 14
	s_cbranch_scc1 .Lpool_skipE
	s_add_u32 s8, s6, 0x1c000
	s_addc_u32 s9, s7, 0
	global_load_dwordx4 v[64:67], v2, s[8:9]
.Lpool_skipE:
	s_lshl_b32 s0, s16, 13
	s_add_u32 s8, s10, s0
	s_addc_u32 s9, s11, 0
	global_load_dwordx4 v[68:71], v2, s[8:9]
	s_add_u32 s8, s8, 0x2000
	s_addc_u32 s9, s9, 0
	global_load_dwordx4 v[72:75], v2, s[8:9]
	s_add_u32 s8, s8, 0x2000
	s_addc_u32 s9, s9, 0
	global_load_dwordx4 v[76:79], v2, s[8:9]
	s_add_u32 s8, s8, 0x2000
	s_addc_u32 s9, s9, 0
	global_load_dwordx4 v[80:83], v2, s[8:9]
	s_add_u32 s8, s8, 0x2000
	s_addc_u32 s9, s9, 0
	global_load_dwordx4 v[84:87], v2, s[8:9]
	s_add_u32 s8, s8, 0x2000
	s_addc_u32 s9, s9, 0
	global_load_dwordx4 v[88:91], v2, s[8:9]
	s_add_u32 s8, s8, 0x2000
	s_addc_u32 s9, s9, 0
	global_load_dwordx4 v[92:95], v2, s[8:9]
	s_add_u32 s8, s8, 0x2000
	s_addc_u32 s9, s9, 0
	global_load_dwordx4 v[96:99], v2, s[8:9]
	s_cmpk_lt_u32 s16, 0x400
	s_cbranch_scc0 .Lpool_st_prompt
	v_readlane_b32 s8, v253, 43
	v_readlane_b32 s9, v253, 44
	s_add_i32 s0, s22, s15
	s_mul_i32 s0, s0, 0x1e000
	s_nop 0
	s_add_u32 s8, s8, s0
	s_addc_u32 s9, s9, 0
	s_nop 3
	s_waitcnt vmcnt(0)
	global_store_dwordx4 v2, v[40:43], s[8:9]
	s_add_u32 s8, s8, 0x2000
	s_addc_u32 s9, s9, 0
	global_store_dwordx4 v2, v[44:47], s[8:9]
	s_add_u32 s8, s8, 0x2000
	s_addc_u32 s9, s9, 0
	global_store_dwordx4 v2, v[48:51], s[8:9]
	s_add_u32 s8, s8, 0x2000
	s_addc_u32 s9, s9, 0
	global_store_dwordx4 v2, v[52:55], s[8:9]
	s_add_u32 s8, s8, 0x2000
	s_addc_u32 s9, s9, 0
	global_store_dwordx4 v2, v[56:59], s[8:9]
	s_add_u32 s8, s8, 0x2000
	s_addc_u32 s9, s9, 0
	global_store_dwordx4 v2, v[60:63], s[8:9]
	s_add_u32 s8, s8, 0x2000
	s_addc_u32 s9, s9, 0
	global_store_dwordx4 v2, v[64:67], s[8:9]
	s_add_u32 s8, s8, 0x2000
	s_addc_u32 s9, s9, 0
	global_store_dwordx4 v2, v[68:71], s[8:9]
	s_add_u32 s8, s8, 0x2000
	s_addc_u32 s9, s9, 0
	global_store_dwordx4 v2, v[72:75], s[8:9]
	s_add_u32 s8, s8, 0x2000
	s_addc_u32 s9, s9, 0
	global_store_dwordx4 v2, v[76:79], s[8:9]
	s_add_u32 s8, s8, 0x2000
	s_addc_u32 s9, s9, 0
	global_store_dwordx4 v2, v[80:83], s[8:9]
	s_add_u32 s8, s8, 0x2000
	s_addc_u32 s9, s9, 0
	global_store_dwordx4 v2, v[84:87], s[8:9]
	s_add_u32 s8, s8, 0x2000
	s_addc_u32 s9, s9, 0
	global_store_dwordx4 v2, v[88:91], s[8:9]
	s_add_u32 s8, s8, 0x2000
	s_addc_u32 s9, s9, 0
	global_store_dwordx4 v2, v[92:95], s[8:9]
	s_add_u32 s8, s8, 0x2000
	s_addc_u32 s9, s9, 0
	global_store_dwordx4 v2, v[96:99], s[8:9]
	s_branch .Lpool_compute
; __device__ void pool_item(const Params& p, int l, int item, const int tid_in) {
;     ...
;             if (prow < MS) {
;                 const int b = prow >> 3, t = prow & 7;
;                 float* np = pout(p) + O_PS + ((size_t)l * 128 + b) * 15 * D + col;
;                 *(f32x4*)(np + (size_t)(7 + t) * D) = p_self;
;                 if (t < 7) *(f32x4*)(np + (size_t)t * D) = p_hist;
;             } else {
;                 const int pr = prow - MS, b = pr / LP, pp = pr % LP;
;                 if (pp >= 2049) *(f32x4*)(pout(p) + O_PP + (((size_t)l * 4 + b) * 15 + (pp - 2049)) * D + col) = p_self;
;             }
;         }
;         asm volatile("" ::: "memory");
;         p_res = sum * (1.0f / cnt) - self; p_self = self; p_hist = hcopy;
.Lpool_st_prompt:
	s_waitcnt vmcnt(0)
	s_cmpk_lt_u32 s13, 0x800
	s_cbranch_scc1 .Lpool_compute
	v_readlane_b32 s8, v253, 41
	v_readlane_b32 s9, v253, 42
	s_add_i32 s0, s24, s15
	s_mul_i32 s0, s0, 0x1e000
	s_nop 0
	s_add_u32 s8, s8, s0
	s_addc_u32 s9, s9, 0
	s_cmpk_eq_u32 s13, 0x800
	s_cbranch_scc0 .Lpool_tail2
	s_nop 3
	global_store_dwordx4 v2, v[72:75], s[8:9]
	s_add_u32 s8, s8, 0x2000
	s_addc_u32 s9, s9, 0
	global_store_dwordx4 v2, v[76:79], s[8:9]
	s_add_u32 s8, s8, 0x2000
	s_addc_u32 s9, s9, 0
	global_store_dwordx4 v2, v[80:83], s[8:9]
	s_add_u32 s8, s8, 0x2000
	s_addc_u32 s9, s9, 0
	global_store_dwordx4 v2, v[84:87], s[8:9]
	s_add_u32 s8, s8, 0x2000
	s_addc_u32 s9, s9, 0
	global_store_dwordx4 v2, v[88:91], s[8:9]
	s_add_u32 s8, s8, 0x2000
	s_addc_u32 s9, s9, 0
	global_store_dwordx4 v2, v[92:95], s[8:9]
	s_add_u32 s8, s8, 0x2000
	s_addc_u32 s9, s9, 0
	global_store_dwordx4 v2, v[96:99], s[8:9]
	s_branch .Lpool_compute
.Lpool_tail2:
	s_add_u32 s8, s8, 0xe000
	s_addc_u32 s9, s9, 0
	global_store_dwordx4 v2, v[68:71], s[8:9]
	s_add_u32 s8, s8, 0x2000
	s_addc_u32 s9, s9, 0
	global_store_dwordx4 v2, v[72:75], s[8:9]
	s_add_u32 s8, s8, 0x2000
	s_addc_u32 s9, s9, 0
	global_store_dwordx4 v2, v[76:79], s[8:9]
	s_add_u32 s8, s8, 0x2000
	s_addc_u32 s9, s9, 0
	global_store_dwordx4 v2, v[80:83], s[8:9]
	s_add_u32 s8, s8, 0x2000
	s_addc_u32 s9, s9, 0
	global_store_dwordx4 v2, v[84:87], s[8:9]
	s_add_u32 s8, s8, 0x2000
	s_addc_u32 s9, s9, 0
	global_store_dwordx4 v2, v[88:91], s[8:9]
	s_add_u32 s8, s8, 0x2000
	s_addc_u32 s9, s9, 0
	global_store_dwordx4 v2, v[92:95], s[8:9]
	s_add_u32 s8, s8, 0x2000
	s_addc_u32 s9, s9, 0
	global_store_dwordx4 v2, v[96:99], s[8:9]
.Lpool_compute:
	v_mov_b64_e32 v[100:101], v[68:69]
	v_mov_b64_e32 v[102:103], v[70:71]
	v_mov_b64_e32 v[104:105], v[72:73]
	v_mov_b64_e32 v[106:107], v[74:75]
	v_mov_b64_e32 v[108:109], v[76:77]
	v_mov_b64_e32 v[110:111], v[78:79]
	v_mov_b64_e32 v[112:113], v[80:81]
	v_mov_b64_e32 v[114:115], v[82:83]
	v_mov_b64_e32 v[116:117], v[84:85]
	v_mov_b64_e32 v[118:119], v[86:87]
	v_mov_b64_e32 v[120:121], v[88:89]
	v_mov_b64_e32 v[122:123], v[90:91]
	v_mov_b64_e32 v[124:125], v[92:93]
	v_mov_b64_e32 v[126:127], v[94:95]
	v_mov_b64_e32 v[128:129], v[96:97]
	v_mov_b64_e32 v[130:131], v[98:99]
	s_cmp_lt_u32 s19, 3
	s_cbranch_scc1 .Lpool_s4
	v_pk_add_f32 v[96:97], v[96:97], v[64:65]
	v_pk_add_f32 v[98:99], v[98:99], v[66:67]
	v_pk_add_f32 v[92:93], v[92:93], v[60:61]
	v_pk_add_f32 v[94:95], v[94:95], v[62:63]
	v_pk_add_f32 v[88:89], v[88:89], v[56:57]
	v_pk_add_f32 v[90:91], v[90:91], v[58:59]
	v_pk_add_f32 v[84:85], v[84:85], v[52:53]
	v_pk_add_f32 v[86:87], v[86:87], v[54:55]
	v_pk_add_f32 v[80:81], v[80:81], v[48:49]
	v_pk_add_f32 v[82:83], v[82:83], v[50:51]
	v_pk_add_f32 v[76:77], v[76:77], v[44:45]
	v_pk_add_f32 v[78:79], v[78:79], v[46:47]
	v_pk_add_f32 v[72:73], v[72:73], v[40:41]
	v_pk_add_f32 v[74:75], v[74:75], v[42:43]
	v_pk_add_f32 v[68:69], v[68:69], v[36:37]
	v_pk_add_f32 v[70:71], v[70:71], v[38:39]
	v_pk_add_f32 v[64:65], v[64:65], v[32:33]
	v_pk_add_f32 v[66:67], v[66:67], v[34:35]
	v_pk_add_f32 v[60:61], v[60:61], v[28:29]
	v_pk_add_f32 v[62:63], v[62:63], v[30:31]
	v_pk_add_f32 v[56:57], v[56:57], v[24:25]
	v_pk_add_f32 v[58:59], v[58:59], v[26:27]
	v_pk_add_f32 v[52:53], v[52:53], v[20:21]
	v_pk_add_f32 v[54:55], v[54:55], v[22:23]
	v_pk_add_f32 v[48:49], v[48:49], v[16:17]
	v_pk_add_f32 v[50:51], v[50:51], v[18:19]
	v_pk_add_f32 v[44:45], v[44:45], v[12:13]
	v_pk_add_f32 v[46:47], v[46:47], v[14:15]
	v_pk_add_f32 v[40:41], v[40:41], v[8:9]
	v_pk_add_f32 v[42:43], v[42:43], v[10:11]
.Lpool_s4:
	s_cmp_lt_u32 s19, 2
	s_cbranch_scc1 .Lpool_s2
	v_pk_add_f32 v[96:97], v[96:97], v[80:81]
	v_pk_add_f32 v[98:99], v[98:99], v[82:83]
	v_pk_add_f32 v[92:93], v[92:93], v[76:77]
	v_pk_add_f32 v[94:95], v[94:95], v[78:79]
	v_pk_add_f32 v[88:89], v[88:89], v[72:73]
	v_pk_add_f32 v[90:91], v[90:91], v[74:75]
	v_pk_add_f32 v[84:85], v[84:85], v[68:69]
	v_pk_add_f32 v[86:87], v[86:87], v[70:71]
	v_pk_add_f32 v[80:81], v[80:81], v[64:65]
	v_pk_add_f32 v[82:83], v[82:83], v[66:67]
	v_pk_add_f32 v[76:77], v[76:77], v[60:61]
	v_pk_add_f32 v[78:79], v[78:79], v[62:63]
	v_pk_add_f32 v[72:73], v[72:73], v[56:57]
	v_pk_add_f32 v[74:75], v[74:75], v[58:59]
	v_pk_add_f32 v[68:69], v[68:69], v[52:53]
	v_pk_add_f32 v[70:71], v[70:71], v[54:55]
	v_pk_add_f32 v[64:65], v[64:65], v[48:49]
	v_pk_add_f32 v[66:67], v[66:67], v[50:51]
	v_pk_add_f32 v[60:61], v[60:61], v[44:45]
	v_pk_add_f32 v[62:63], v[62:63], v[46:47]
	v_pk_add_f32 v[56:57], v[56:57], v[40:41]
	v_pk_add_f32 v[58:59], v[58:59], v[42:43]
; __device__ __forceinline__ unsigned pk_bf16(float lo, float hi) { unsigned r; asm volatile("v_cvt_pk_bf16_f32 %0, %1, %2" : "=v"(r) : "v"(lo), "v"(hi)); return r; }
; __device__ void pool_item(const Params& p, int l, int item, const int tid_in) {
;     ...
;         if (rr > 0) {
;             const int prow = row - 1;
;             u32x2 o; o.x = pk_bf16(p_res[0], p_res[1]); o.y = pk_bf16(p_res[2], p_res[3]);
;             *(u32x2*)(pooled + (size_t)prow * D + col) = o;
;             if (prow < MS) {
;                 const int b = prow >> 3, t = prow & 7;
;                 float* np = pout(p) + O_PS + ((size_t)l * 128 + b) * 15 * D + col;
;                 *(f32x4*)(np + (size_t)(7 + t) * D) = p_self;
;                 if (t < 7) *(f32x4*)(np + (size_t)t * D) = p_hist;
;             } else {
;                 const int pr = prow - MS, b = pr / LP, pp = pr % LP;
;                 if (pp >= 2049) *(f32x4*)(pout(p) + O_PP + (((size_t)l * 4 + b) * 15 + (pp - 2049)) * D + col) = p_self;
;             }
;         }
;         asm volatile("" ::: "memory");
;         p_res = sum * (1.0f / cnt) - self; p_self = self; p_hist = hcopy;
.Lpool_s2:
	s_cmp_lt_u32 s19, 1
	s_cbranch_scc1 .Lpool_s1
	v_pk_add_f32 v[96:97], v[96:97], v[88:89]
	v_pk_add_f32 v[98:99], v[98:99], v[90:91]
	v_pk_add_f32 v[92:93], v[92:93], v[84:85]
	v_pk_add_f32 v[94:95], v[94:95], v[86:87]
	v_pk_add_f32 v[88:89], v[88:89], v[80:81]
	v_pk_add_f32 v[90:91], v[90:91], v[82:83]
	v_pk_add_f32 v[84:85], v[84:85], v[76:77]
	v_pk_add_f32 v[86:87], v[86:87], v[78:79]
	v_pk_add_f32 v[80:81], v[80:81], v[72:73]
	v_pk_add_f32 v[82:83], v[82:83], v[74:75]
	v_pk_add_f32 v[76:77], v[76:77], v[68:69]
	v_pk_add_f32 v[78:79], v[78:79], v[70:71]
	v_pk_add_f32 v[72:73], v[72:73], v[64:65]
	v_pk_add_f32 v[74:75], v[74:75], v[66:67]
	v_pk_add_f32 v[68:69], v[68:69], v[60:61]
	v_pk_add_f32 v[70:71], v[70:71], v[62:63]
	v_pk_add_f32 v[64:65], v[64:65], v[56:57]
	v_pk_add_f32 v[66:67], v[66:67], v[58:59]
.Lpool_s1:
	v_pk_add_f32 v[96:97], v[96:97], v[92:93]
	v_pk_add_f32 v[98:99], v[98:99], v[94:95]
	v_pk_add_f32 v[92:93], v[92:93], v[88:89]
	v_pk_add_f32 v[94:95], v[94:95], v[90:91]
	v_pk_add_f32 v[88:89], v[88:89], v[84:85]
	v_pk_add_f32 v[90:91], v[90:91], v[86:87]
	v_pk_add_f32 v[84:85], v[84:85], v[80:81]
	v_pk_add_f32 v[86:87], v[86:87], v[82:83]
	v_pk_add_f32 v[80:81], v[80:81], v[76:77]
	v_pk_add_f32 v[82:83], v[82:83], v[78:79]
	v_pk_add_f32 v[76:77], v[76:77], v[72:73]
	v_pk_add_f32 v[78:79], v[78:79], v[74:75]
	v_pk_add_f32 v[72:73], v[72:73], v[68:69]
	v_pk_add_f32 v[74:75], v[74:75], v[70:71]
	v_pk_add_f32 v[68:69], v[68:69], v[64:65]
	v_pk_add_f32 v[70:71], v[70:71], v[66:67]
	v_readlane_b32 s8, v253, 34
	v_readlane_b32 s9, v253, 35
	s_lshl_b32 s0, s16, 12
	s_nop 0
	s_add_u32 s8, s8, s0
	s_addc_u32 s9, s9, 0
	s_add_i32 s0, s13, 1
	s_min_u32 s0, s0, s18
	v_cvt_f32_u32_e32 v4, s0
	v_rcp_f32_e32 v4, v4
	s_nop 0
	v_fma_f32 v68, v68, v4, -v100
	v_fma_f32 v69, v69, v4, -v101
	v_fma_f32 v70, v70, v4, -v102
	v_fma_f32 v71, v71, v4, -v103
	v_cvt_pk_bf16_f32 v68, v68, v69
	v_cvt_pk_bf16_f32 v69, v70, v71
	global_store_dwordx2 v3, v[68:69], s[8:9]
	s_add_u32 s8, s8, 0x1000
	s_addc_u32 s9, s9, 0
	s_add_i32 s0, s13, 2
	s_min_u32 s0, s0, s18
	v_cvt_f32_u32_e32 v4, s0
	v_rcp_f32_e32 v4, v4
	s_nop 0
	v_fma_f32 v72, v72, v4, -v104
	v_fma_f32 v73, v73, v4, -v105
	v_fma_f32 v74, v74, v4, -v106
	v_fma_f32 v75, v75, v4, -v107
	v_cvt_pk_bf16_f32 v72, v72, v73
	v_cvt_pk_bf16_f32 v73, v74, v75
	global_store_dwordx2 v3, v[72:73], s[8:9]
	s_add_u32 s8, s8, 0x1000
	s_addc_u32 s9, s9, 0
	s_add_i32 s0, s13, 3
	s_min_u32 s0, s0, s18
	v_cvt_f32_u32_e32 v4, s0
	v_rcp_f32_e32 v4, v4
	s_nop 0
	v_fma_f32 v76, v76, v4, -v108
	v_fma_f32 v77, v77, v4, -v109
	v_fma_f32 v78, v78, v4, -v110
	v_fma_f32 v79, v79, v4, -v111
	v_cvt_pk_bf16_f32 v76, v76, v77
	v_cvt_pk_bf16_f32 v77, v78, v79
	global_store_dwordx2 v3, v[76:77], s[8:9]
	s_add_u32 s8, s8, 0x1000
	s_addc_u32 s9, s9, 0
	s_add_i32 s0, s13, 4
	s_min_u32 s0, s0, s18
	v_cvt_f32_u32_e32 v4, s0
	v_rcp_f32_e32 v4, v4
	s_nop 0
	v_fma_f32 v80, v80, v4, -v112
	v_fma_f32 v81, v81, v4, -v113
	v_fma_f32 v82, v82, v4, -v114
	v_fma_f32 v83, v83, v4, -v115
	v_cvt_pk_bf16_f32 v80, v80, v81
	v_cvt_pk_bf16_f32 v81, v82, v83
	global_store_dwordx2 v3, v[80:81], s[8:9]
	s_add_u32 s8, s8, 0x1000
	s_addc_u32 s9, s9, 0
	s_add_i32 s0, s13, 5
	s_min_u32 s0, s0, s18
	v_cvt_f32_u32_e32 v4, s0
	v_rcp_f32_e32 v4, v4
	s_nop 0
	v_fma_f32 v84, v84, v4, -v116
	v_fma_f32 v85, v85, v4, -v117
	v_fma_f32 v86, v86, v4, -v118
	v_fma_f32 v87, v87, v4, -v119
	v_cvt_pk_bf16_f32 v84, v84, v85
	v_cvt_pk_bf16_f32 v85, v86, v87
	global_store_dwordx2 v3, v[84:85], s[8:9]
	s_add_u32 s8, s8, 0x1000
	s_addc_u32 s9, s9, 0
	s_add_i32 s0, s13, 6
	s_min_u32 s0, s0, s18
	v_cvt_f32_u32_e32 v4, s0
	v_rcp_f32_e32 v4, v4
	s_nop 0
	v_fma_f32 v88, v88, v4, -v120
	v_fma_f32 v89, v89, v4, -v121
	v_fma_f32 v90, v90, v4, -v122
	v_fma_f32 v91, v91, v4, -v123
	v_cvt_pk_bf16_f32 v88, v88, v89
	v_cvt_pk_bf16_f32 v89, v90, v91
	global_store_dwordx2 v3, v[88:89], s[8:9]
	s_add_u32 s8, s8, 0x1000
	s_addc_u32 s9, s9, 0
	s_add_i32 s0, s13, 7
	s_min_u32 s0, s0, s18
	v_cvt_f32_u32_e32 v4, s0
	v_rcp_f32_e32 v4, v4
	s_nop 0
	v_fma_f32 v92, v92, v4, -v124
	v_fma_f32 v93, v93, v4, -v125
	v_fma_f32 v94, v94, v4, -v126
	v_fma_f32 v95, v95, v4, -v127
	v_cvt_pk_bf16_f32 v92, v92, v93
	v_cvt_pk_bf16_f32 v93, v94, v95
	global_store_dwordx2 v3, v[92:93], s[8:9]
	s_add_u32 s8, s8, 0x1000
	s_addc_u32 s9, s9, 0
	s_add_i32 s0, s13, 8
	s_min_u32 s0, s0, s18
	v_cvt_f32_u32_e32 v4, s0
	v_rcp_f32_e32 v4, v4
	s_nop 0
	v_fma_f32 v96, v96, v4, -v128
	v_fma_f32 v97, v97, v4, -v129
	v_fma_f32 v98, v98, v4, -v130
	v_fma_f32 v99, v99, v4, -v131
	v_cvt_pk_bf16_f32 v96, v96, v97
	v_cvt_pk_bf16_f32 v97, v98, v99
	global_store_dwordx2 v3, v[96:97], s[8:9]
	s_add_i32 s16, s16, 8
	s_and_b32 s0, s16, 8
	s_cmp_lg_u32 s0, 0
	s_cbranch_scc1 .Lpool_half
	s_branch .LBB0_451
